# prologue deferral: w1d->bf16 conversion moved from the prologue to GU1's idle last-round workgroups (wave-level queue, 2 blocks per pull)
# speedup vs baseline: 1.0165x; 1.0072x over previous
.LBB0_7:
	s_or_b64 exec, exec, s[14:15]
	s_movk_i32 s93, 0x1600
	v_cmp_gt_i32_e64 s[94:95], s93, v176
	v_add_u32_e32 v176, s42, v176
	v_cmp_le_i32_e64 s[66:67], s93, v176
	v_mov_b32_e32 v177, 0xb00
	s_and_b64 vcc, s[94:95], s[66:67]
	s_nop 1
	v_cndmask_b32_e32 v177, 0, v177, vcc
	v_add_u32_e32 v176, v176, v177
	v_lshl_add_u32 v170, v177, 3, v170
	v_cmp_lt_i32_e32 vcc, s65, v176
	s_or_b64 s[34:35], vcc, s[34:35]
	v_add_u32_e32 v170, s33, v170
	s_andn2_b64 exec, exec, s[34:35]
	s_cbranch_execz .LBB0_115

.LBB0_210:
	s_mov_b64 exec, -1
	v_readlane_b32 s98, v253, 0
	v_readlane_b32 s99, v253, 23
	s_nop 3
	s_cmpk_lg_u32 s99, 0x100
	s_cbranch_scc1 .Lw1d_go
	s_cmpk_lt_u32 s98, 0xac
	s_cbranch_scc1 .Lw1d_done
.Lw1d_go:
	v_readlane_b32 s0, v253, 21
	v_readlane_b32 s1, v253, 22
	s_nop 3
	s_sub_u32 s0, s0, 0xe0
	s_subb_u32 s1, s1, 0
	s_load_dwordx2 s[8:9], s[0:1], 0x50
	s_add_u32 s6, s86, 0xc600
	s_addc_u32 s7, s87, 0
	v_and_b32_e32 v6, 15, v0
	v_and_b32_e32 v7, 48, v0
	v_lshlrev_b32_e32 v8, 13, v7
	v_lshl_or_b32 v8, v6, 4, v8
	v_lshlrev_b32_e32 v9, 2, v6
	v_and_b32_e32 v9, 32, v9
	v_lshlrev_b32_e32 v10, 4, v6
	v_and_b32_e32 v10, 16, v10
	v_lshlrev_b32_e32 v11, 1, v6
	v_and_b32_e32 v11, 12, v11
	v_or3_b32 v9, v9, v10, v11
	v_mul_u32_u24_e32 v9, 0x2c00, v9
	v_lshl_add_u32 v12, v7, 1, v9
	v_add_u32_e32 v13, 0x2c00, v12
	v_add_u32_e32 v14, 0x5800, v12
	v_add_u32_e32 v15, 0x8400, v12
	v_mov_b32_e32 v16, 0
	v_mov_b32_e32 v17, 1
	s_mov_b64 exec, 1
	global_atomic_add v18, v16, v17, s[6:7] sc0
	s_mov_b64 exec, -1
	s_waitcnt vmcnt(0) lgkmcnt(0)
.Lw1d_loop:
	v_readfirstlane_b32 s98, v18
	s_nop 3
	s_cmpk_ge_u32 s98, 0x580
	s_cbranch_scc1 .Lw1d_done
	s_lshr_b32 s99, s98, 4
	s_and_b32 s100, s98, 15
	s_lshl_b32 s101, s99, 19
	s_lshl_b32 s0, s100, 9
	s_add_u32 s0, s0, s101
	s_add_u32 s0, s8, s0
	s_addc_u32 s1, s9, 0
	s_mul_i32 s2, s100, 0x160000
	s_lshl_b32 s3, s99, 7
	s_add_u32 s2, s2, s3
	s_add_u32 s2, s2, 0x2d60200
	s_add_u32 s2, s86, s2
	s_addc_u32 s3, s87, 0
	s_add_u32 s4, s2, 0xb0000
	s_addc_u32 s5, s3, 0
	global_load_dwordx4 v[154:157], v8, s[0:1] nt
	global_load_dwordx4 v[204:207], v8, s[0:1] offset:256 nt
	s_add_u32 s0, s0, 0x2000
	s_addc_u32 s1, s1, 0
	global_load_dwordx4 v[158:161], v8, s[0:1] nt
	global_load_dwordx4 v[208:211], v8, s[0:1] offset:256 nt
	s_add_u32 s0, s0, 0x2000
	s_addc_u32 s1, s1, 0
	global_load_dwordx4 v[162:165], v8, s[0:1] nt
	global_load_dwordx4 v[212:215], v8, s[0:1] offset:256 nt
	s_add_u32 s0, s0, 0x2000
	s_addc_u32 s1, s1, 0
	global_load_dwordx4 v[166:169], v8, s[0:1] nt
	global_load_dwordx4 v[216:219], v8, s[0:1] offset:256 nt
	s_add_u32 s0, s0, 0x2000
	s_addc_u32 s1, s1, 0
	global_load_dwordx4 v[170:173], v8, s[0:1] nt
	global_load_dwordx4 v[220:223], v8, s[0:1] offset:256 nt
	s_add_u32 s0, s0, 0x2000
	s_addc_u32 s1, s1, 0
	global_load_dwordx4 v[174:177], v8, s[0:1] nt
	global_load_dwordx4 v[224:227], v8, s[0:1] offset:256 nt
	s_add_u32 s0, s0, 0x2000
	s_addc_u32 s1, s1, 0
	global_load_dwordx4 v[178:181], v8, s[0:1] nt
	global_load_dwordx4 v[228:231], v8, s[0:1] offset:256 nt
	s_add_u32 s0, s0, 0x2000
	s_addc_u32 s1, s1, 0
	global_load_dwordx4 v[182:185], v8, s[0:1] nt
	global_load_dwordx4 v[232:235], v8, s[0:1] offset:256 nt
	s_add_u32 s0, s0, 0x2000
	s_addc_u32 s1, s1, 0
	global_load_dwordx4 v[186:189], v8, s[0:1] nt
	global_load_dwordx4 v[236:239], v8, s[0:1] offset:256 nt
	s_add_u32 s0, s0, 0x2000
	s_addc_u32 s1, s1, 0
	global_load_dwordx4 v[190:193], v8, s[0:1] nt
	global_load_dwordx4 v[240:243], v8, s[0:1] offset:256 nt
	s_add_u32 s0, s0, 0x2000
	s_addc_u32 s1, s1, 0
	global_load_dwordx4 v[194:197], v8, s[0:1] nt
	global_load_dwordx4 v[244:247], v8, s[0:1] offset:256 nt
	s_add_u32 s0, s0, 0x2000
	s_addc_u32 s1, s1, 0
	global_load_dwordx4 v[198:201], v8, s[0:1] nt
	global_load_dwordx4 v[248:251], v8, s[0:1] offset:256 nt
	s_add_u32 s0, s0, 0x2000
	s_addc_u32 s1, s1, 0
	global_load_dwordx4 v[130:133], v8, s[0:1] nt
	global_load_dwordx4 v[50:53], v8, s[0:1] offset:256 nt
	s_add_u32 s0, s0, 0x2000
	s_addc_u32 s1, s1, 0
	global_load_dwordx4 v[134:137], v8, s[0:1] nt
	global_load_dwordx4 v[54:57], v8, s[0:1] offset:256 nt
	s_add_u32 s0, s0, 0x2000
	s_addc_u32 s1, s1, 0
	global_load_dwordx4 v[138:141], v8, s[0:1] nt
	global_load_dwordx4 v[58:61], v8, s[0:1] offset:256 nt
	s_add_u32 s0, s0, 0x2000
	s_addc_u32 s1, s1, 0
	global_load_dwordx4 v[142:145], v8, s[0:1] nt
	global_load_dwordx4 v[62:65], v8, s[0:1] offset:256 nt
	s_mov_b64 exec, 1
	global_atomic_add v18, v16, v17, s[6:7] sc0
	s_mov_b64 exec, -1
	s_waitcnt vmcnt(1)
	v_cvt_pk_bf16_f32 v20, v154, v158
	v_cvt_pk_bf16_f32 v21, v162, v166
	v_cvt_pk_bf16_f32 v22, v170, v174
	v_cvt_pk_bf16_f32 v23, v178, v182
	global_store_dwordx4 v12, v[20:23], s[2:3]
	v_cvt_pk_bf16_f32 v24, v186, v190
	v_cvt_pk_bf16_f32 v25, v194, v198
	v_cvt_pk_bf16_f32 v26, v130, v134
	v_cvt_pk_bf16_f32 v27, v138, v142
	global_store_dwordx4 v12, v[24:27], s[2:3] offset:16
	v_cvt_pk_bf16_f32 v28, v155, v159
	v_cvt_pk_bf16_f32 v29, v163, v167
	v_cvt_pk_bf16_f32 v30, v171, v175
	v_cvt_pk_bf16_f32 v31, v179, v183
	global_store_dwordx4 v13, v[28:31], s[2:3]
	v_cvt_pk_bf16_f32 v32, v187, v191
	v_cvt_pk_bf16_f32 v33, v195, v199
	v_cvt_pk_bf16_f32 v34, v131, v135
	v_cvt_pk_bf16_f32 v35, v139, v143
	global_store_dwordx4 v13, v[32:35], s[2:3] offset:16
	v_cvt_pk_bf16_f32 v36, v156, v160
	v_cvt_pk_bf16_f32 v37, v164, v168
	v_cvt_pk_bf16_f32 v38, v172, v176
	v_cvt_pk_bf16_f32 v39, v180, v184
	global_store_dwordx4 v14, v[36:39], s[2:3]
	v_cvt_pk_bf16_f32 v40, v188, v192
	v_cvt_pk_bf16_f32 v41, v196, v200
	v_cvt_pk_bf16_f32 v42, v132, v136
	v_cvt_pk_bf16_f32 v43, v140, v144
	global_store_dwordx4 v14, v[40:43], s[2:3] offset:16
	v_cvt_pk_bf16_f32 v20, v157, v161
	v_cvt_pk_bf16_f32 v21, v165, v169
	v_cvt_pk_bf16_f32 v22, v173, v177
	v_cvt_pk_bf16_f32 v23, v181, v185
	global_store_dwordx4 v15, v[20:23], s[2:3]
	v_cvt_pk_bf16_f32 v24, v189, v193
	v_cvt_pk_bf16_f32 v25, v197, v201
	v_cvt_pk_bf16_f32 v26, v133, v137
	v_cvt_pk_bf16_f32 v27, v141, v145
	global_store_dwordx4 v15, v[24:27], s[2:3] offset:16
	v_cvt_pk_bf16_f32 v28, v204, v208
	v_cvt_pk_bf16_f32 v29, v212, v216
	v_cvt_pk_bf16_f32 v30, v220, v224
	v_cvt_pk_bf16_f32 v31, v228, v232
	global_store_dwordx4 v12, v[28:31], s[4:5]
	v_cvt_pk_bf16_f32 v32, v236, v240
	v_cvt_pk_bf16_f32 v33, v244, v248
	v_cvt_pk_bf16_f32 v34, v50, v54
	v_cvt_pk_bf16_f32 v35, v58, v62
	global_store_dwordx4 v12, v[32:35], s[4:5] offset:16
	v_cvt_pk_bf16_f32 v36, v205, v209
	v_cvt_pk_bf16_f32 v37, v213, v217
	v_cvt_pk_bf16_f32 v38, v221, v225
	v_cvt_pk_bf16_f32 v39, v229, v233
	global_store_dwordx4 v13, v[36:39], s[4:5]
	v_cvt_pk_bf16_f32 v40, v237, v241
	v_cvt_pk_bf16_f32 v41, v245, v249
	v_cvt_pk_bf16_f32 v42, v51, v55
	v_cvt_pk_bf16_f32 v43, v59, v63
	global_store_dwordx4 v13, v[40:43], s[4:5] offset:16
	v_cvt_pk_bf16_f32 v20, v206, v210
	v_cvt_pk_bf16_f32 v21, v214, v218
	v_cvt_pk_bf16_f32 v22, v222, v226
	v_cvt_pk_bf16_f32 v23, v230, v234
	global_store_dwordx4 v14, v[20:23], s[4:5]
	v_cvt_pk_bf16_f32 v24, v238, v242
	v_cvt_pk_bf16_f32 v25, v246, v250
	v_cvt_pk_bf16_f32 v26, v52, v56
	v_cvt_pk_bf16_f32 v27, v60, v64
	global_store_dwordx4 v14, v[24:27], s[4:5] offset:16
	v_cvt_pk_bf16_f32 v28, v207, v211
	v_cvt_pk_bf16_f32 v29, v215, v219
	v_cvt_pk_bf16_f32 v30, v223, v227
	v_cvt_pk_bf16_f32 v31, v231, v235
	global_store_dwordx4 v15, v[28:31], s[4:5]
	v_cvt_pk_bf16_f32 v32, v239, v243
	v_cvt_pk_bf16_f32 v33, v247, v251
	v_cvt_pk_bf16_f32 v34, v53, v57
	v_cvt_pk_bf16_f32 v35, v61, v65
	global_store_dwordx4 v15, v[32:35], s[4:5] offset:16
	s_waitcnt vmcnt(16)
	s_branch .Lw1d_loop
